# single attention copy for both P2 paths; attention epilogue Z loads and merged-GEMM epilogue gate loads issued up front with counted waits
# speedup vs baseline: 1.0472x; 1.0100x over previous
; #define VMW() asm volatile("s_waitcnt vmcnt(0)" ::: "memory")
; #define SLOAD_H(Kp, Vp, k0) do { S.st_v0 = load8(ROWK(Vp, k0, sr)); S.st_v1 = load8(ROWK(Vp, k0, 32 + sr));              \
;                          S.st_k0 = load8(ROWK(Kp, k0, sr)); S.st_k1 = load8(ROWK(Kp, k0, 32 + sr)); } while (0)
; #define SWRITE_HK(bf) do { OPQ_TID(); const int kws_ = KSWZ(sr_, sc_ * 2); *(bf16x8*)(K_lds + (bf) * SHM_K + kws_) = S.st_k0; *(bf16x8*)(K_lds + (bf) * SHM_K + kws_ + 32 * 256) = S.st_k1; } while (0)
; __device__ __forceinline__ void fox_prime(const BlockRef& cur, char* lds, char* cbcur, Seam& S) {
;     const int tid = threadIdx.x, wid = __builtin_amdgcn_readfirstlane(tid >> 6), lane = tid & 63, r32 = lane & 31, hi = lane >> 5;
;     const int sr = tid >> 4, sc = (tid & 15) * 8; char* K_lds = lds + 2 * SHM_V;
;     for (int d0 = 0; d0 < 8; ++d0) S.qr[d0] = load8(cur.Q + (size_t)(wid * QBLK + r32) * QP + d0 * 16 + hi * 8);
;     SLOAD_H(cur.K, cur.V, cur.P0 + QB - KVBLK); VMW(); SWRITE_HK(0);
;     fill_cb(cur.C, cur.P0, cbcur);
;     __syncthreads();
; }
; __device__ __forceinline__ void fox_phase(char* lds, const Tensors& T, int vcu, int G) {
;     constexpr int total = 64 * 8;
;     int L = vcu; if (L >= total) return;
;     int pass = 0, par = 0;
;     char* cb0 = lds + LDS_CB_OFF;
;     BlockRef cur = make_ref(T, L >> 3, L & 7);
;     Seam S;
;     fox_prime(cur, lds, cb0, S);
.Lattn_entry:
	s_cmpk_gt_i32 s86, 0x1ff
	s_cbranch_scc1 .LBB0_263
	s_ashr_i32 s4, s86, 6
	s_ashr_i32 s5, s4, 31
	s_lshl_b32 s13, s86, 8
	s_lshl_b64 s[6:7], s[4:5], 12
	s_and_b32 s84, s13, 0x700
	s_or_b32 s6, s6, s84
	s_ashr_i32 s12, s86, 3
	s_lshl_b64 s[14:15], s[6:7], 12
	s_add_u32 s13, s40, s14
	s_addc_u32 s15, s41, s15
	s_lshl_b32 s14, s12, 7
	s_and_b32 s14, s14, 0x380
	s_lshl_b32 s18, s14, 1
	s_add_u32 s14, s13, s18
	s_addc_u32 s15, s15, 0
	s_lshl_b64 s[16:17], s[4:5], 23
	s_add_u32 s4, s34, s16
	s_addc_u32 s5, s35, s17
	s_add_u32 s4, s4, s18
	s_addc_u32 s5, s5, 0
	s_add_u32 s13, s54, s16
	s_addc_u32 s16, s55, s17
	s_add_u32 s74, s13, s18
	s_addc_u32 s75, s16, 0
	s_ashr_i32 s13, s12, 31
	s_lshl_b64 s[12:13], s[12:13], 14
	s_add_u32 s12, s58, s12
	v_readfirstlane_b32 s16, v0
	s_addc_u32 s13, s59, s13
	s_lshr_b32 s16, s16, 1
	v_and_b32_e32 v1, 31, v0
	s_and_b32 s16, s16, 0x7fffffe0
	v_or_b32_e32 v4, s16, v1
	v_mov_b32_e32 v5, 0
	v_lshlrev_b64 v[2:3], 12, v[4:5]
	v_lshrrev_b32_e32 v4, 1, v0
	v_lshl_add_u64 v[2:3], s[14:15], 0, v[2:3]
	v_and_b32_e32 v4, 16, v4
	v_lshl_add_u64 v[2:3], v[2:3], 0, v[4:5]
	global_load_dwordx4 v[158:161], v[2:3], off offset:2048
	global_load_dwordx4 v[154:157], v[2:3], off offset:2080
	global_load_dwordx4 v[150:153], v[2:3], off offset:2112
	global_load_dwordx4 v[146:149], v[2:3], off offset:2144
	global_load_dwordx4 v[142:145], v[2:3], off offset:2176
	global_load_dwordx4 v[138:141], v[2:3], off offset:2208
	global_load_dwordx4 v[134:137], v[2:3], off offset:2240
	global_load_dwordx4 v[130:133], v[2:3], off offset:2272
	v_lshrrev_b32_e32 v192, 4, v0
	v_or_b32_e32 v4, 0xc0, v192
	v_lshlrev_b32_e32 v2, 3, v0
	v_or_b32_e32 v4, s84, v4
	v_and_b32_e32 v3, 0x78, v2
	v_lshlrev_b32_e32 v4, 11, v4
	v_or_b32_e32 v193, 0xe0, v192
	v_lshl_add_u64 v[6:7], s[74:75], 0, v[4:5]
	v_lshlrev_b32_e32 v182, 1, v3
	v_mov_b32_e32 v183, v5
	v_or_b32_e32 v3, s84, v193
	v_lshl_add_u64 v[12:13], v[6:7], 0, v[182:183]
	v_lshlrev_b32_e32 v6, 11, v3
	v_mov_b32_e32 v7, v5
	v_lshl_add_u64 v[8:9], s[74:75], 0, v[6:7]
	v_lshl_add_u64 v[4:5], s[4:5], 0, v[4:5]
	v_lshl_add_u64 v[6:7], s[4:5], 0, v[6:7]
	v_lshl_add_u64 v[14:15], v[8:9], 0, v[182:183]
	v_lshl_add_u64 v[4:5], v[4:5], 0, v[182:183]
	v_lshl_add_u64 v[8:9], v[6:7], 0, v[182:183]
	global_load_dwordx4 v[4:7], v[4:5], off
	s_nop 0
	global_load_dwordx4 v[8:11], v[8:9], off
	s_nop 0
	global_load_dwordx4 v[102:105], v[12:13], off
	global_load_dwordx4 v[98:101], v[14:15], off
	v_mov_b32_e32 v3, v0
	s_waitcnt vmcnt(0)
	s_movk_i32 s16, 0xf0
	v_lshlrev_b32_e32 v12, 4, v3
	v_and_b32_e32 v3, 0x70, v3
	v_lshlrev_b32_e32 v239, 2, v0
	s_add_i32 s17, s84, 0x100
	v_and_b32_e32 v13, 0xffffff00, v12
	v_bitop3_b32 v3, v12, v3, s16 bitop3:0x6c
	v_add3_u32 v3, 0, v13, v3
	v_cmp_le_u32_e32 vcc, s17, v239
	s_waitcnt vmcnt(0)
	ds_write_b128 v3, v[4:7] offset:32768
	ds_write_b128 v3, v[8:11] offset:40960
	s_and_saveexec_b64 s[16:17], vcc
	s_xor_b64 s[16:17], exec, s[16:17]
	v_lshlrev_b32_e32 v3, 5, v0
	s_andn2_saveexec_b64 s[16:17], s[16:17]
	s_cbranch_execz .LBB0_223
	s_lshl_b32 s19, s84, 2
	v_mov_b32_e32 v3, s19
	v_lshlrev_b32_e32 v4, 2, v239
	global_load_dword v8, v3, s[12:13]
	s_nop 0
	global_load_dwordx4 v[4:7], v4, s[12:13]
	v_lshlrev_b32_e32 v3, 5, v0
	v_add_u32_e32 v10, 0, v3
	v_add_u32_e32 v12, 0x10800, v10
	s_mov_b32 s19, 0x413504f3
	v_mov_b32_e32 v9, 0
	s_waitcnt vmcnt(0)
	v_sub_f32_e32 v4, v8, v4
	v_sub_f32_e32 v5, v8, v5
	v_sub_f32_e32 v6, v8, v6
	v_sub_f32_e32 v7, v8, v7
	v_mul_f32_e32 v8, 0x413504f3, v4
	v_mul_f32_e32 v10, 0x413504f3, v5
	v_mul_f32_e32 v11, 0x413504f3, v6
	v_mul_f32_e32 v13, 0x413504f3, v7
	v_and_b32_e32 v14, 0xffff0000, v8
	v_and_b32_e32 v15, 0xffff0000, v10
	v_and_b32_e32 v16, 0xffff0000, v11
	v_and_b32_e32 v17, 0xffff0000, v13
	v_fma_f32 v4, v4, s19, -v14
	v_fma_f32 v5, v5, s19, -v15
	v_fma_f32 v14, v6, s19, -v16
	v_fma_f32 v7, v7, s19, -v17
	v_and_b32_e32 v15, 0xffff0000, v5
	v_and_b32_e32 v16, 0xffff0000, v14
	v_and_b32_e32 v17, 0xffff0000, v7
	v_and_b32_e32 v6, 0xffff0000, v4
	v_sub_f32_e32 v5, v5, v15
	v_sub_f32_e32 v14, v14, v16
	v_sub_f32_e32 v7, v7, v17
	v_sub_f32_e32 v18, v4, v6
	v_or_b32_sdwa v4, v6, v8 dst_sel:DWORD dst_unused:UNUSED_PAD src0_sel:DWORD src1_sel:WORD_1
	v_or_b32_sdwa v6, v15, v10 dst_sel:DWORD dst_unused:UNUSED_PAD src0_sel:DWORD src1_sel:WORD_1
	v_or_b32_sdwa v8, v16, v11 dst_sel:DWORD dst_unused:UNUSED_PAD src0_sel:DWORD src1_sel:WORD_1
	v_or_b32_sdwa v10, v17, v13 dst_sel:DWORD dst_unused:UNUSED_PAD src0_sel:DWORD src1_sel:WORD_1
	v_cvt_pk_bf16_f32 v11, v18, v9
	v_cvt_pk_bf16_f32 v13, v5, v9
	v_cvt_pk_bf16_f32 v14, v14, v9
	v_cvt_pk_bf16_f32 v15, v7, v9
	s_nop 0
	v_and_b32_e32 v5, 0xffff, v11
	v_and_b32_e32 v7, 0xffff, v13
	v_and_b32_e32 v9, 0xffff, v14
	v_and_b32_e32 v11, 0xffff, v15
	ds_write_b128 v12, v[4:7]
	ds_write_b128 v12, v[8:11] offset:16

; #define SBAR() __builtin_amdgcn_sched_barrier(0)
; __device__ __forceinline__ int crow(int r, int hi) { return (r & 3) + 8 * (r >> 2) + 4 * hi; }
; __device__ __forceinline__ unsigned cvtpk(float lo, float hi) { unsigned r; asm volatile("v_cvt_pk_bf16_f32 %0, %1, %2" : "=v"(r) : "v"(lo), "v"(hi)); return r; }
; #define SEAM_K0() do { VMWN(NQL); SWRITE_HK(0); SBAR(); } while (0)
; __device__ __forceinline__ void fox_block(const BlockRef& cur, const BlockRef& nxt, char* lds, char* cbcur, char* cbnxt, Seam& S) {
;     ...
;     SBAR(); SEAM_K0();
;     if (hi == 0) li_l[r32] = l_reg; asm volatile("s_waitcnt lgkmcnt(0)" ::: "memory");
;     float rli[16];
; #pragma unroll
;     for (int r = 0; r < 16; ++r) rli[r] = __builtin_amdgcn_rcpf(li_l[crow(r, hi)]);
;     {
;         int ln = lane; asm volatile("" : "+v"(ln)); const int r32e = ln & 31, hie = ln >> 5;
;         char* stg = lds + LDS_STG_OFF + wid * 4352;
;         bf16* Ow = cur.O + (size_t)(wid * QBLK) * QP; const bf16* Zw = cur.Z + (size_t)(wid * QBLK) * ZP;
; #pragma unroll
;         for (int half = 0; half < 2; ++half) {
; #pragma unroll
;             for (int rr = 0; rr < 8; ++rr) { const int r = half * 8 + rr; const int lrow = (rr & 3) + 8 * (rr >> 2) + 4 * hie;
; #pragma unroll
;                 for (int d0 = 0; d0 < 4; ++d0) *(unsigned short*)(stg + lrow * 272 + (d0 * 32 + r32e) * 2) = (unsigned short)cvtpk(o[d0][r] * rli[r], 0.f); }
;             asm volatile("s_waitcnt lgkmcnt(0)" ::: "memory");
; #pragma unroll
;             for (int it = 0; it < 4; ++it) { const int lrow = it * 4 + (ln >> 4), ch = ln & 15, grow = half * 16 + lrow;
;                 const u32x4 ov = *(const u32x4*)(stg + lrow * 272 + ch * 16); const u32x4 z = *(const u32x4*)(Zw + (size_t)grow * ZP + ch * 8);
.LBB0_258:
	v_mov_b32_e32 v66, v0
	s_waitcnt vmcnt(8)
	s_nop 0
	v_lshlrev_b32_e32 v67, 4, v66
	v_and_b32_e32 v66, 0x70, v66
	v_and_b32_e32 v68, 0xffffff00, v67
	v_bitop3_b32 v66, v67, v66, s79 bitop3:0x6c
	v_add3_u32 v66, 0, v68, v66
	s_waitcnt vmcnt(9)
	ds_write_b128 v66, v[106:109] offset:32768
	s_waitcnt vmcnt(8)
	ds_write_b128 v66, v[110:113] offset:40960
	s_and_saveexec_b64 s[4:5], s[6:7]
	ds_write_b32 v212, v114
	s_or_b64 exec, exec, s[4:5]
	s_waitcnt lgkmcnt(0)
	ds_read_b128 v[66:69], v211
	ds_read_b128 v[70:73], v211 offset:32
	s_mulk_i32 s69, 0x1100
	s_add_i32 s4, s69, 0
	s_add_i32 s69, s4, 0x18800
	s_waitcnt lgkmcnt(1)
	v_rcp_f32_e32 v77, v66
	s_lshl_b64 s[4:5], s[14:15], 12
	v_rcp_f32_e32 v81, v67
	v_mov_b32_e32 v74, v201
	s_add_u32 s4, s70, s4
	v_rcp_f32_e32 v84, v68
	v_rcp_f32_e32 v85, v69
	s_waitcnt lgkmcnt(0)
	v_rcp_f32_e32 v86, v70
	v_rcp_f32_e32 v87, v71
	v_rcp_f32_e32 v88, v72
	v_rcp_f32_e32 v89, v73
	ds_read_b128 v[66:69], v211 offset:64
	ds_read_b128 v[70:73], v211 offset:96
	s_addc_u32 s5, s71, s5
	s_lshl_b64 s[70:71], s[14:15], 11
	v_lshlrev_b32_e32 v75, 1, v74
	s_add_u32 s70, s72, s70
	v_ashrrev_i32_e32 v90, 3, v74
	v_and_b32_e32 v75, 62, v75
	v_ashrrev_i32_e32 v76, 4, v74
	v_lshlrev_b32_e32 v74, 4, v74
	s_addc_u32 s71, s73, s71
	v_and_b32_e32 v78, 0xffffffc, v90
	v_add_u32_e32 v80, s69, v75
	v_and_b32_e32 v82, 0xf0, v74
	v_mov_b32_e32 v83, v183
	v_mul_f32_e32 v2, v2, v77
	v_lshl_add_u64 v[74:75], s[70:71], 0, v[82:83]
	v_lshlrev_b32_e32 v216, 11, v76
	v_mov_b32_e32 v217, 0
	v_lshl_add_u64 v[214:215], v[74:75], 0, v[216:217]
	v_mov_b32_e32 v216, 0x2000
	global_load_dwordx4 v[166:169], v[214:215], off
	v_lshl_add_u64 v[214:215], v[214:215], 0, v[216:217]
	global_load_dwordx4 v[170:173], v[214:215], off
	v_lshl_add_u64 v[214:215], v[214:215], 0, v[216:217]
	global_load_dwordx4 v[174:177], v[214:215], off
	v_lshl_add_u64 v[214:215], v[214:215], 0, v[216:217]
	global_load_dwordx4 v[178:181], v[214:215], off
	v_lshl_add_u64 v[214:215], v[214:215], 0, v[216:217]
	global_load_dwordx4 v[240:243], v[214:215], off
	v_lshl_add_u64 v[214:215], v[214:215], 0, v[216:217]
	global_load_dwordx4 v[244:247], v[214:215], off
	v_lshl_add_u64 v[214:215], v[214:215], 0, v[216:217]
	global_load_dwordx4 v[248:251], v[214:215], off
	v_lshl_add_u64 v[214:215], v[214:215], 0, v[216:217]
	global_load_dwordx4 v[252:255], v[214:215], off
	v_mad_u64_u32 v[78:79], s[70:71], v78, s80, v[80:81]
	v_cvt_pk_bf16_f32 v2, v2, v183
	ds_write_b16 v78, v2
	v_mul_f32_e32 v2, v50, v77
	v_cvt_pk_bf16_f32 v2, v2, v183
	ds_write_b16 v78, v2 offset:64
	v_mul_f32_e32 v2, v34, v77
	v_cvt_pk_bf16_f32 v2, v2, v183
	ds_write_b16 v78, v2 offset:128
	v_mul_f32_e32 v2, v18, v77
	v_cvt_pk_bf16_f32 v2, v2, v183
	ds_write_b16 v78, v2 offset:192
	v_mul_f32_e32 v2, v3, v81
	v_cvt_pk_bf16_f32 v2, v2, v183
	ds_write_b16 v78, v2 offset:272
	v_mul_f32_e32 v2, v51, v81
	v_cvt_pk_bf16_f32 v2, v2, v183
	ds_write_b16 v78, v2 offset:336
	v_mul_f32_e32 v2, v35, v81
	v_cvt_pk_bf16_f32 v2, v2, v183
	ds_write_b16 v78, v2 offset:400
	v_mul_f32_e32 v2, v19, v81
	v_cvt_pk_bf16_f32 v2, v2, v183
	ds_write_b16 v78, v2 offset:464
	v_mul_f32_e32 v2, v4, v84
	v_cvt_pk_bf16_f32 v2, v2, v183
	ds_write_b16 v78, v2 offset:544
	v_mul_f32_e32 v2, v52, v84
	v_cvt_pk_bf16_f32 v2, v2, v183
	ds_write_b16 v78, v2 offset:608
	v_mul_f32_e32 v2, v36, v84
	v_cvt_pk_bf16_f32 v2, v2, v183
	ds_write_b16 v78, v2 offset:672
	v_mul_f32_e32 v2, v20, v84
	v_cvt_pk_bf16_f32 v2, v2, v183
	ds_write_b16 v78, v2 offset:736
	v_or_b32_e32 v2, 3, v90
	v_mad_u64_u32 v[18:19], s[70:71], v2, s80, v[80:81]
	v_mul_f32_e32 v2, v5, v85
	v_cvt_pk_bf16_f32 v2, v2, v183
	ds_write_b16 v18, v2
	v_mul_f32_e32 v2, v53, v85
	v_cvt_pk_bf16_f32 v2, v2, v183
	ds_write_b16 v18, v2 offset:64
	v_mul_f32_e32 v2, v37, v85
	v_cvt_pk_bf16_f32 v2, v2, v183
	ds_write_b16 v18, v2 offset:128
	v_mul_f32_e32 v2, v21, v85
	v_cvt_pk_bf16_f32 v2, v2, v183
	ds_write_b16 v18, v2 offset:192
	v_mul_f32_e32 v2, v6, v86
	v_cvt_pk_bf16_f32 v2, v2, v183
	ds_write_b16 v78, v2 offset:2176
	v_mul_f32_e32 v2, v54, v86
	v_cvt_pk_bf16_f32 v2, v2, v183
	ds_write_b16 v78, v2 offset:2240
	v_mul_f32_e32 v2, v38, v86
	v_cvt_pk_bf16_f32 v2, v2, v183
	ds_write_b16 v78, v2 offset:2304
	v_mul_f32_e32 v2, v22, v86
	v_cvt_pk_bf16_f32 v2, v2, v183
	ds_write_b16 v78, v2 offset:2368
	v_mul_f32_e32 v2, v7, v87
	v_cvt_pk_bf16_f32 v2, v2, v183
	ds_write_b16 v78, v2 offset:2448
	v_mul_f32_e32 v2, v55, v87
	v_cvt_pk_bf16_f32 v2, v2, v183
	ds_write_b16 v78, v2 offset:2512
	v_mul_f32_e32 v2, v39, v87
	v_cvt_pk_bf16_f32 v2, v2, v183
	ds_write_b16 v78, v2 offset:2576
	v_mul_f32_e32 v2, v23, v87
	v_cvt_pk_bf16_f32 v2, v2, v183
	ds_write_b16 v78, v2 offset:2640
	v_mul_f32_e32 v2, v8, v88
	v_cvt_pk_bf16_f32 v2, v2, v183
	ds_write_b16 v78, v2 offset:2720
	v_mul_f32_e32 v2, v56, v88
	v_cvt_pk_bf16_f32 v2, v2, v183
	ds_write_b16 v78, v2 offset:2784
	v_mul_f32_e32 v2, v40, v88
	v_cvt_pk_bf16_f32 v2, v2, v183
	ds_write_b16 v78, v2 offset:2848
	v_mul_f32_e32 v2, v24, v88
	v_cvt_pk_bf16_f32 v2, v2, v183
	ds_write_b16 v78, v2 offset:2912
	v_mul_f32_e32 v2, v9, v89
	v_cvt_pk_bf16_f32 v2, v2, v183
	ds_write_b16 v18, v2 offset:2176
	v_mul_f32_e32 v2, v57, v89
	v_cvt_pk_bf16_f32 v2, v2, v183
	ds_write_b16 v18, v2 offset:2240
	v_mul_f32_e32 v2, v41, v89
	v_cvt_pk_bf16_f32 v2, v2, v183
	ds_write_b16 v18, v2 offset:2304
	v_mul_f32_e32 v2, v25, v89
	v_cvt_pk_bf16_f32 v2, v2, v183
	v_ashrrev_i32_e32 v77, 31, v76
	ds_write_b16 v18, v2 offset:2368
	v_lshlrev_b64 v[2:3], 11, v[76:77]
	s_waitcnt lgkmcnt(0)
; __device__ __forceinline__ unsigned cvtpk(float lo, float hi) { unsigned r; asm volatile("v_cvt_pk_bf16_f32 %0, %1, %2" : "=v"(r) : "v"(lo), "v"(hi)); return r; }
; __device__ __forceinline__ void fox_block(const BlockRef& cur, const BlockRef& nxt, char* lds, char* cbcur, char* cbnxt, Seam& S) {
;     ...
;         for (int half = 0; half < 2; ++half) {
; #pragma unroll
;             for (int rr = 0; rr < 8; ++rr) { const int r = half * 8 + rr; const int lrow = (rr & 3) + 8 * (rr >> 2) + 4 * hie;
; #pragma unroll
;                 for (int d0 = 0; d0 < 4; ++d0) *(unsigned short*)(stg + lrow * 272 + (d0 * 32 + r32e) * 2) = (unsigned short)cvtpk(o[d0][r] * rli[r], 0.f); }
;             asm volatile("s_waitcnt lgkmcnt(0)" ::: "memory");
; #pragma unroll
;             for (int it = 0; it < 4; ++it) { const int lrow = it * 4 + (ln >> 4), ch = ln & 15, grow = half * 16 + lrow;
;                 const u32x4 ov = *(const u32x4*)(stg + lrow * 272 + ch * 16); const u32x4 z = *(const u32x4*)(Zw + (size_t)grow * ZP + ch * 8);
;                 u32x4 w;
;                 w.x = cvtpk(__uint_as_float(ov.x << 16) * __uint_as_float(z.x << 16), __uint_as_float(ov.x & 0xffff0000u) * __uint_as_float(z.x & 0xffff0000u));
;                 w.y = cvtpk(__uint_as_float(ov.y << 16) * __uint_as_float(z.y << 16), __uint_as_float(ov.y & 0xffff0000u) * __uint_as_float(z.y & 0xffff0000u));
;                 w.z = cvtpk(__uint_as_float(ov.z << 16) * __uint_as_float(z.z << 16), __uint_as_float(ov.z & 0xffff0000u) * __uint_as_float(z.z & 0xffff0000u));
;                 w.w = cvtpk(__uint_as_float(ov.w << 16) * __uint_as_float(z.w << 16), __uint_as_float(ov.w & 0xffff0000u) * __uint_as_float(z.w & 0xffff0000u));
;                 *(u32x4*)(Ow + (size_t)grow * QP + ch * 8) = w; }
	v_lshl_add_u64 v[2:3], v[74:75], 0, v[2:3]
	v_mul_lo_u32 v2, v76, s80
	v_add3_u32 v4, s69, v82, v2
	ds_read_b128 v[20:23], v4
	v_lshl_add_u64 v[2:3], s[4:5], 0, v[82:83]
	v_add_u32_e32 v24, 4, v76
	v_ashrrev_i32_e32 v25, 31, v24
	v_add_u32_e32 v34, 8, v76
	s_waitcnt lgkmcnt(0)
	v_lshlrev_b32_e32 v5, 16, v20
	s_add_i32 s14, s68, 0x100
	v_cmp_gt_i32_e32 vcc, s14, v239
	s_waitcnt vmcnt(7)
	v_mov_b32_e32 v6, v166
	v_mov_b32_e32 v7, v167
	v_mov_b32_e32 v8, v168
	v_mov_b32_e32 v9, v169
	v_lshlrev_b32_e32 v19, 16, v6
	v_mul_f32_e32 v5, v19, v5
	v_and_b32_e32 v6, 0xffff0000, v6
	v_and_b32_e32 v19, 0xffff0000, v20
	v_mul_f32_e32 v6, v6, v19
	v_cvt_pk_bf16_f32 v6, v5, v6
	v_lshlrev_b32_e32 v5, 16, v21
	v_lshlrev_b32_e32 v19, 16, v7
	v_mul_f32_e32 v5, v19, v5
	v_and_b32_e32 v7, 0xffff0000, v7
	v_and_b32_e32 v19, 0xffff0000, v21
	v_mul_f32_e32 v7, v7, v19
	v_cvt_pk_bf16_f32 v7, v5, v7
	v_lshlrev_b32_e32 v5, 16, v22
	v_lshlrev_b32_e32 v19, 16, v8
	v_mul_f32_e32 v5, v19, v5
	v_and_b32_e32 v8, 0xffff0000, v8
	v_and_b32_e32 v19, 0xffff0000, v22
	v_mul_f32_e32 v8, v8, v19
	v_cvt_pk_bf16_f32 v8, v5, v8
	v_lshlrev_b32_e32 v5, 16, v23
	v_lshlrev_b32_e32 v19, 16, v9
	v_mul_f32_e32 v5, v19, v5
	v_and_b32_e32 v9, 0xffff0000, v9
	v_and_b32_e32 v19, 0xffff0000, v23
	v_lshlrev_b64 v[20:21], 12, v[76:77]
	v_mul_f32_e32 v9, v9, v19
	v_lshl_add_u64 v[20:21], v[2:3], 0, v[20:21]
	v_cvt_pk_bf16_f32 v9, v5, v9
	global_store_dwordx4 v[20:21], v[6:9], off
	ds_read_b128 v[20:23], v4 offset:1088
	s_waitcnt lgkmcnt(0)
	v_lshlrev_b32_e32 v5, 16, v20
	v_lshlrev_b64 v[6:7], 11, v[24:25]
	v_lshl_add_u64 v[6:7], v[74:75], 0, v[6:7]
	v_and_b32_e32 v19, 0xffff0000, v20
	v_lshlrev_b32_e32 v20, 16, v21
	v_and_b32_e32 v21, 0xffff0000, v21
	v_lshlrev_b64 v[24:25], 12, v[24:25]
	v_lshlrev_b32_e32 v35, 16, v22
	v_and_b32_e32 v22, 0xffff0000, v22
	v_lshlrev_b32_e32 v36, 16, v23
	v_and_b32_e32 v23, 0xffff0000, v23
	v_lshl_add_u64 v[24:25], v[2:3], 0, v[24:25]
	s_waitcnt vmcnt(7)
	v_mov_b32_e32 v6, v170
	v_mov_b32_e32 v7, v171
	v_mov_b32_e32 v8, v172
	v_mov_b32_e32 v9, v173
	v_lshlrev_b32_e32 v37, 16, v6
	v_and_b32_e32 v6, 0xffff0000, v6
	v_lshlrev_b32_e32 v38, 16, v7
	v_and_b32_e32 v7, 0xffff0000, v7
	v_lshlrev_b32_e32 v39, 16, v8
	v_and_b32_e32 v8, 0xffff0000, v8
	v_lshlrev_b32_e32 v40, 16, v9
	v_and_b32_e32 v9, 0xffff0000, v9
	v_mul_f32_e32 v6, v6, v19
	v_mul_f32_e32 v7, v7, v21
	v_mul_f32_e32 v5, v37, v5
	v_mul_f32_e32 v19, v38, v20
	v_mul_f32_e32 v20, v39, v35
	v_mul_f32_e32 v8, v8, v22
	v_mul_f32_e32 v9, v9, v23
	v_cvt_pk_bf16_f32 v6, v5, v6
	v_cvt_pk_bf16_f32 v7, v19, v7
	v_ashrrev_i32_e32 v35, 31, v34
	v_mul_f32_e32 v21, v40, v36
	v_cvt_pk_bf16_f32 v8, v20, v8
	v_cvt_pk_bf16_f32 v9, v21, v9
	global_store_dwordx4 v[24:25], v[6:9], off
	ds_read_b128 v[20:23], v4 offset:2176
	v_add_u32_e32 v24, 12, v76
	v_lshlrev_b64 v[6:7], 11, v[34:35]
	v_lshl_add_u64 v[6:7], v[74:75], 0, v[6:7]
	v_ashrrev_i32_e32 v25, 31, v24
	v_lshlrev_b64 v[34:35], 12, v[34:35]
	s_waitcnt lgkmcnt(0)
	v_lshlrev_b32_e32 v5, 16, v20
	v_and_b32_e32 v19, 0xffff0000, v20
	v_lshlrev_b32_e32 v20, 16, v21
	v_and_b32_e32 v21, 0xffff0000, v21
	v_lshlrev_b32_e32 v38, 16, v22
	v_and_b32_e32 v22, 0xffff0000, v22
	v_lshlrev_b32_e32 v39, 16, v23
	v_and_b32_e32 v23, 0xffff0000, v23
	v_lshlrev_b64 v[36:37], 11, v[24:25]
	v_lshl_add_u64 v[34:35], v[2:3], 0, v[34:35]
	v_lshl_add_u64 v[36:37], v[74:75], 0, v[36:37]
	s_waitcnt vmcnt(7)
	v_mov_b32_e32 v6, v174
	v_mov_b32_e32 v7, v175
	v_mov_b32_e32 v8, v176
	v_mov_b32_e32 v9, v177
	v_lshlrev_b32_e32 v40, 16, v6
	v_and_b32_e32 v6, 0xffff0000, v6
	v_lshlrev_b32_e32 v41, 16, v7
	v_and_b32_e32 v7, 0xffff0000, v7
	v_lshlrev_b32_e32 v50, 16, v8
	v_and_b32_e32 v8, 0xffff0000, v8
	v_lshlrev_b32_e32 v51, 16, v9
	v_and_b32_e32 v9, 0xffff0000, v9
	v_mul_f32_e32 v6, v6, v19
	v_mul_f32_e32 v7, v7, v21
	v_mul_f32_e32 v8, v8, v22
	v_mul_f32_e32 v9, v9, v23
	v_mul_f32_e32 v5, v40, v5
	v_mul_f32_e32 v19, v41, v20
	v_mul_f32_e32 v20, v50, v38
	v_mul_f32_e32 v21, v51, v39
	v_cvt_pk_bf16_f32 v6, v5, v6
	v_cvt_pk_bf16_f32 v7, v19, v7
	v_cvt_pk_bf16_f32 v8, v20, v8
	v_cvt_pk_bf16_f32 v9, v21, v9
	global_store_dwordx4 v[34:35], v[6:9], off
	v_rcp_f32_e32 v5, v66
	v_rcp_f32_e32 v19, v67
	v_rcp_f32_e32 v34, v68
	v_rcp_f32_e32 v35, v69
	v_mul_f32_e32 v40, v10, v5
	v_mul_f32_e32 v41, v58, v5
	v_mul_f32_e32 v42, v42, v5
	v_mul_f32_e32 v5, v26, v5
	v_mul_f32_e32 v26, v11, v19
	v_mul_f32_e32 v50, v59, v19
	v_mul_f32_e32 v43, v43, v19
	v_mul_f32_e32 v19, v27, v19
	v_mul_f32_e32 v27, v12, v34
	v_mul_f32_e32 v51, v60, v34
	v_mul_f32_e32 v44, v44, v34
	v_mul_f32_e32 v28, v28, v34
	v_mul_f32_e32 v34, v13, v35
	ds_read_b128 v[10:13], v4 offset:3264
	v_rcp_f32_e32 v36, v70
	v_rcp_f32_e32 v37, v71
	v_rcp_f32_e32 v38, v72
	v_rcp_f32_e32 v39, v73
	v_lshlrev_b64 v[22:23], 12, v[24:25]
	v_mul_f32_e32 v52, v61, v35
	v_mul_f32_e32 v45, v45, v35
	v_mul_f32_e32 v29, v29, v35
	v_mul_f32_e32 v14, v14, v36
	v_mul_f32_e32 v35, v62, v36
	v_mul_f32_e32 v46, v46, v36
	v_mul_f32_e32 v30, v30, v36
	v_mul_f32_e32 v15, v15, v37
	v_mul_f32_e32 v36, v63, v37
	v_mul_f32_e32 v47, v47, v37
	v_mul_f32_e32 v31, v31, v37
	v_mul_f32_e32 v16, v16, v38
	v_mul_f32_e32 v37, v64, v38
	v_mul_f32_e32 v48, v48, v38
	v_mul_f32_e32 v32, v32, v38
	v_mul_f32_e32 v17, v17, v39
	v_mul_f32_e32 v38, v65, v39
	v_mul_f32_e32 v49, v49, v39
	v_mul_f32_e32 v33, v33, v39
	s_waitcnt lgkmcnt(0)
	v_lshlrev_b32_e32 v39, 16, v10
	v_and_b32_e32 v10, 0xffff0000, v10
	v_lshlrev_b32_e32 v53, 16, v11
	v_and_b32_e32 v11, 0xffff0000, v11
	v_lshlrev_b32_e32 v54, 16, v12
	v_and_b32_e32 v12, 0xffff0000, v12
	v_lshlrev_b32_e32 v55, 16, v13
	v_and_b32_e32 v13, 0xffff0000, v13
	v_lshl_add_u64 v[22:23], v[2:3], 0, v[22:23]
	v_add_u32_e32 v20, 16, v76
	v_ashrrev_i32_e32 v21, 31, v20
	v_lshlrev_b64 v[24:25], 11, v[20:21]
	v_lshl_add_u64 v[24:25], v[74:75], 0, v[24:25]
	s_waitcnt vmcnt(7)
; __device__ __forceinline__ unsigned cvtpk(float lo, float hi) { unsigned r; asm volatile("v_cvt_pk_bf16_f32 %0, %1, %2" : "=v"(r) : "v"(lo), "v"(hi)); return r; }
; __device__ __forceinline__ void fox_block(const BlockRef& cur, const BlockRef& nxt, char* lds, char* cbcur, char* cbnxt, Seam& S) {
;     ...
;         for (int half = 0; half < 2; ++half) {
; #pragma unroll
;             for (int rr = 0; rr < 8; ++rr) { const int r = half * 8 + rr; const int lrow = (rr & 3) + 8 * (rr >> 2) + 4 * hie;
; #pragma unroll
;                 for (int d0 = 0; d0 < 4; ++d0) *(unsigned short*)(stg + lrow * 272 + (d0 * 32 + r32e) * 2) = (unsigned short)cvtpk(o[d0][r] * rli[r], 0.f); }
;             asm volatile("s_waitcnt lgkmcnt(0)" ::: "memory");
; #pragma unroll
;             for (int it = 0; it < 4; ++it) { const int lrow = it * 4 + (ln >> 4), ch = ln & 15, grow = half * 16 + lrow;
;                 const u32x4 ov = *(const u32x4*)(stg + lrow * 272 + ch * 16); const u32x4 z = *(const u32x4*)(Zw + (size_t)grow * ZP + ch * 8);
;                 u32x4 w;
;                 w.x = cvtpk(__uint_as_float(ov.x << 16) * __uint_as_float(z.x << 16), __uint_as_float(ov.x & 0xffff0000u) * __uint_as_float(z.x & 0xffff0000u));
;                 w.y = cvtpk(__uint_as_float(ov.y << 16) * __uint_as_float(z.y << 16), __uint_as_float(ov.y & 0xffff0000u) * __uint_as_float(z.y & 0xffff0000u));
;                 w.z = cvtpk(__uint_as_float(ov.z << 16) * __uint_as_float(z.z << 16), __uint_as_float(ov.z & 0xffff0000u) * __uint_as_float(z.z & 0xffff0000u));
;                 w.w = cvtpk(__uint_as_float(ov.w << 16) * __uint_as_float(z.w << 16), __uint_as_float(ov.w & 0xffff0000u) * __uint_as_float(z.w & 0xffff0000u));
;                 *(u32x4*)(Ow + (size_t)grow * QP + ch * 8) = w; }
	v_mov_b32_e32 v6, v178
	v_mov_b32_e32 v7, v179
	v_mov_b32_e32 v8, v180
	v_mov_b32_e32 v9, v181
	v_lshlrev_b32_e32 v56, 16, v6
	v_and_b32_e32 v6, 0xffff0000, v6
	v_lshlrev_b32_e32 v57, 16, v7
	v_and_b32_e32 v7, 0xffff0000, v7
	v_lshlrev_b32_e32 v58, 16, v8
	v_and_b32_e32 v8, 0xffff0000, v8
	v_lshlrev_b32_e32 v59, 16, v9
	v_and_b32_e32 v9, 0xffff0000, v9
	v_mul_f32_e32 v6, v6, v10
	v_mul_f32_e32 v7, v7, v11
	v_mul_f32_e32 v8, v8, v12
	v_mul_f32_e32 v9, v9, v13
	v_mul_f32_e32 v39, v56, v39
	v_mul_f32_e32 v10, v57, v53
	v_mul_f32_e32 v11, v58, v54
	v_mul_f32_e32 v12, v59, v55
	v_cvt_pk_bf16_f32 v6, v39, v6
	v_cvt_pk_bf16_f32 v7, v10, v7
	v_cvt_pk_bf16_f32 v8, v11, v8
	v_cvt_pk_bf16_f32 v9, v12, v9
	global_store_dwordx4 v[22:23], v[6:9], off
	s_waitcnt lgkmcnt(0)
	s_nop 1
	v_cvt_pk_bf16_f32 v6, v40, v183
	ds_write_b16 v78, v6
	v_cvt_pk_bf16_f32 v6, v41, v183
	ds_write_b16 v78, v6 offset:64
	v_cvt_pk_bf16_f32 v6, v42, v183
	ds_write_b16 v78, v6 offset:128
	v_cvt_pk_bf16_f32 v5, v5, v183
	ds_write_b16 v78, v5 offset:192
	v_cvt_pk_bf16_f32 v5, v26, v183
	ds_write_b16 v78, v5 offset:272
	v_cvt_pk_bf16_f32 v5, v50, v183
	ds_write_b16 v78, v5 offset:336
	v_cvt_pk_bf16_f32 v5, v43, v183
	ds_write_b16 v78, v5 offset:400
	v_cvt_pk_bf16_f32 v5, v19, v183
	ds_write_b16 v78, v5 offset:464
	v_cvt_pk_bf16_f32 v5, v27, v183
	ds_write_b16 v78, v5 offset:544
	v_cvt_pk_bf16_f32 v5, v51, v183
	ds_write_b16 v78, v5 offset:608
	v_cvt_pk_bf16_f32 v5, v44, v183
	ds_write_b16 v78, v5 offset:672
	v_cvt_pk_bf16_f32 v5, v28, v183
	ds_write_b16 v78, v5 offset:736
	v_cvt_pk_bf16_f32 v5, v34, v183
	ds_write_b16 v18, v5
	v_cvt_pk_bf16_f32 v5, v52, v183
	ds_write_b16 v18, v5 offset:64
	v_cvt_pk_bf16_f32 v5, v45, v183
	ds_write_b16 v18, v5 offset:128
	v_cvt_pk_bf16_f32 v5, v29, v183
	ds_write_b16 v18, v5 offset:192
	v_cvt_pk_bf16_f32 v5, v14, v183
	ds_write_b16 v78, v5 offset:2176
	v_cvt_pk_bf16_f32 v5, v35, v183
	ds_write_b16 v78, v5 offset:2240
	v_cvt_pk_bf16_f32 v5, v46, v183
	ds_write_b16 v78, v5 offset:2304
	v_cvt_pk_bf16_f32 v5, v30, v183
	ds_write_b16 v78, v5 offset:2368
	v_cvt_pk_bf16_f32 v5, v15, v183
	ds_write_b16 v78, v5 offset:2448
	v_cvt_pk_bf16_f32 v5, v36, v183
	ds_write_b16 v78, v5 offset:2512
	v_cvt_pk_bf16_f32 v5, v47, v183
	ds_write_b16 v78, v5 offset:2576
	v_cvt_pk_bf16_f32 v5, v31, v183
	ds_write_b16 v78, v5 offset:2640
	v_cvt_pk_bf16_f32 v5, v16, v183
	ds_write_b16 v78, v5 offset:2720
	v_cvt_pk_bf16_f32 v5, v37, v183
	ds_write_b16 v78, v5 offset:2784
	v_cvt_pk_bf16_f32 v5, v48, v183
	ds_write_b16 v78, v5 offset:2848
	v_cvt_pk_bf16_f32 v5, v32, v183
	ds_write_b16 v78, v5 offset:2912
	v_cvt_pk_bf16_f32 v5, v17, v183
	ds_write_b16 v18, v5 offset:2176
	v_cvt_pk_bf16_f32 v5, v38, v183
	ds_write_b16 v18, v5 offset:2240
	v_cvt_pk_bf16_f32 v5, v49, v183
	ds_write_b16 v18, v5 offset:2304
	v_cvt_pk_bf16_f32 v5, v33, v183
	ds_write_b16 v18, v5 offset:2368
	s_waitcnt lgkmcnt(0)
	ds_read_b128 v[10:13], v4
	v_add_u32_e32 v14, 20, v76
	v_ashrrev_i32_e32 v15, 31, v14
	v_lshlrev_b64 v[16:17], 12, v[20:21]
	v_lshlrev_b64 v[18:19], 11, v[14:15]
	s_waitcnt lgkmcnt(0)
	v_lshlrev_b32_e32 v5, 16, v10
	v_and_b32_e32 v10, 0xffff0000, v10
	v_lshlrev_b32_e32 v20, 16, v11
	v_and_b32_e32 v11, 0xffff0000, v11
	v_lshlrev_b32_e32 v21, 16, v12
	v_and_b32_e32 v12, 0xffff0000, v12
	v_lshlrev_b32_e32 v22, 16, v13
	v_and_b32_e32 v13, 0xffff0000, v13
	v_lshl_add_u64 v[16:17], v[2:3], 0, v[16:17]
	v_lshl_add_u64 v[18:19], v[74:75], 0, v[18:19]
	v_lshlrev_b64 v[14:15], 12, v[14:15]
	v_lshl_add_u64 v[14:15], v[2:3], 0, v[14:15]
	s_waitcnt vmcnt(7)
	v_mov_b32_e32 v6, v240
	v_mov_b32_e32 v7, v241
	v_mov_b32_e32 v8, v242
	v_mov_b32_e32 v9, v243
	v_lshlrev_b32_e32 v23, 16, v6
	v_and_b32_e32 v6, 0xffff0000, v6
	v_lshlrev_b32_e32 v24, 16, v7
	v_and_b32_e32 v7, 0xffff0000, v7
	v_lshlrev_b32_e32 v25, 16, v8
	v_and_b32_e32 v8, 0xffff0000, v8
	v_lshlrev_b32_e32 v26, 16, v9
	v_and_b32_e32 v9, 0xffff0000, v9
	v_mul_f32_e32 v6, v6, v10
	v_mul_f32_e32 v7, v7, v11
	v_mul_f32_e32 v8, v8, v12
	v_mul_f32_e32 v9, v9, v13
	v_mul_f32_e32 v5, v23, v5
	v_mul_f32_e32 v10, v24, v20
	v_mul_f32_e32 v11, v25, v21
	v_mul_f32_e32 v12, v26, v22
	v_cvt_pk_bf16_f32 v6, v5, v6
	v_cvt_pk_bf16_f32 v7, v10, v7
	v_cvt_pk_bf16_f32 v8, v11, v8
	v_cvt_pk_bf16_f32 v9, v12, v9
	global_store_dwordx4 v[16:17], v[6:9], off
	ds_read_b128 v[10:13], v4 offset:1088
	v_add_u32_e32 v16, 24, v76
	v_ashrrev_i32_e32 v17, 31, v16
	v_lshlrev_b64 v[18:19], 11, v[16:17]
	v_lshl_add_u64 v[18:19], v[74:75], 0, v[18:19]
	s_waitcnt lgkmcnt(0)
; __device__ __forceinline__ unsigned cvtpk(float lo, float hi) { unsigned r; asm volatile("v_cvt_pk_bf16_f32 %0, %1, %2" : "=v"(r) : "v"(lo), "v"(hi)); return r; }
; __device__ __forceinline__ void fox_block(const BlockRef& cur, const BlockRef& nxt, char* lds, char* cbcur, char* cbnxt, Seam& S) {
;     ...
;         for (int half = 0; half < 2; ++half) {
; #pragma unroll
;             for (int rr = 0; rr < 8; ++rr) { const int r = half * 8 + rr; const int lrow = (rr & 3) + 8 * (rr >> 2) + 4 * hie;
; #pragma unroll
;                 for (int d0 = 0; d0 < 4; ++d0) *(unsigned short*)(stg + lrow * 272 + (d0 * 32 + r32e) * 2) = (unsigned short)cvtpk(o[d0][r] * rli[r], 0.f); }
;             asm volatile("s_waitcnt lgkmcnt(0)" ::: "memory");
; #pragma unroll
;             for (int it = 0; it < 4; ++it) { const int lrow = it * 4 + (ln >> 4), ch = ln & 15, grow = half * 16 + lrow;
;                 const u32x4 ov = *(const u32x4*)(stg + lrow * 272 + ch * 16); const u32x4 z = *(const u32x4*)(Zw + (size_t)grow * ZP + ch * 8);
;                 u32x4 w;
;                 w.x = cvtpk(__uint_as_float(ov.x << 16) * __uint_as_float(z.x << 16), __uint_as_float(ov.x & 0xffff0000u) * __uint_as_float(z.x & 0xffff0000u));
;                 w.y = cvtpk(__uint_as_float(ov.y << 16) * __uint_as_float(z.y << 16), __uint_as_float(ov.y & 0xffff0000u) * __uint_as_float(z.y & 0xffff0000u));
;                 w.z = cvtpk(__uint_as_float(ov.z << 16) * __uint_as_float(z.z << 16), __uint_as_float(ov.z & 0xffff0000u) * __uint_as_float(z.z & 0xffff0000u));
;                 w.w = cvtpk(__uint_as_float(ov.w << 16) * __uint_as_float(z.w << 16), __uint_as_float(ov.w & 0xffff0000u) * __uint_as_float(z.w & 0xffff0000u));
;                 *(u32x4*)(Ow + (size_t)grow * QP + ch * 8) = w; }
;             asm volatile("s_waitcnt lgkmcnt(0)" ::: "memory");
;         }
;     }
;     fill_cb(nxt.C, nxt.P0, cbnxt);
	v_lshlrev_b32_e32 v5, 16, v10
	v_and_b32_e32 v10, 0xffff0000, v10
	v_lshlrev_b32_e32 v20, 16, v11
	v_and_b32_e32 v11, 0xffff0000, v11
	v_lshlrev_b32_e32 v21, 16, v12
	v_and_b32_e32 v12, 0xffff0000, v12
	v_lshlrev_b32_e32 v22, 16, v13
	v_and_b32_e32 v13, 0xffff0000, v13
	v_lshlrev_b64 v[16:17], 12, v[16:17]
	v_lshl_add_u64 v[16:17], v[2:3], 0, v[16:17]
	s_waitcnt vmcnt(7)
	v_mov_b32_e32 v6, v244
	v_mov_b32_e32 v7, v245
	v_mov_b32_e32 v8, v246
	v_mov_b32_e32 v9, v247
	v_lshlrev_b32_e32 v23, 16, v6
	v_and_b32_e32 v6, 0xffff0000, v6
	v_lshlrev_b32_e32 v24, 16, v7
	v_and_b32_e32 v7, 0xffff0000, v7
	v_lshlrev_b32_e32 v25, 16, v8
	v_and_b32_e32 v8, 0xffff0000, v8
	v_lshlrev_b32_e32 v26, 16, v9
	v_and_b32_e32 v9, 0xffff0000, v9
	v_mul_f32_e32 v6, v6, v10
	v_mul_f32_e32 v7, v7, v11
	v_mul_f32_e32 v8, v8, v12
	v_mul_f32_e32 v9, v9, v13
	v_mul_f32_e32 v5, v23, v5
	v_mul_f32_e32 v10, v24, v20
	v_mul_f32_e32 v11, v25, v21
	v_mul_f32_e32 v12, v26, v22
	v_cvt_pk_bf16_f32 v6, v5, v6
	v_cvt_pk_bf16_f32 v7, v10, v7
	v_cvt_pk_bf16_f32 v8, v11, v8
	v_cvt_pk_bf16_f32 v9, v12, v9
	global_store_dwordx4 v[14:15], v[6:9], off
	ds_read_b128 v[10:13], v4 offset:2176
	v_add_u32_e32 v14, 28, v76
	v_ashrrev_i32_e32 v15, 31, v14
	v_lshlrev_b64 v[18:19], 11, v[14:15]
	v_lshl_add_u64 v[18:19], v[74:75], 0, v[18:19]
	s_waitcnt lgkmcnt(0)
	v_lshlrev_b32_e32 v5, 16, v10
	v_and_b32_e32 v10, 0xffff0000, v10
	v_lshlrev_b32_e32 v20, 16, v11
	v_and_b32_e32 v11, 0xffff0000, v11
	v_lshlrev_b32_e32 v21, 16, v12
	v_and_b32_e32 v12, 0xffff0000, v12
	v_lshlrev_b32_e32 v22, 16, v13
	v_and_b32_e32 v13, 0xffff0000, v13
	v_lshlrev_b64 v[14:15], 12, v[14:15]
	v_lshl_add_u64 v[2:3], v[2:3], 0, v[14:15]
	s_waitcnt vmcnt(7)
	v_mov_b32_e32 v6, v248
	v_mov_b32_e32 v7, v249
	v_mov_b32_e32 v8, v250
	v_mov_b32_e32 v9, v251
	v_lshlrev_b32_e32 v23, 16, v6
	v_and_b32_e32 v6, 0xffff0000, v6
	v_lshlrev_b32_e32 v24, 16, v7
	v_and_b32_e32 v7, 0xffff0000, v7
	v_lshlrev_b32_e32 v25, 16, v8
	v_and_b32_e32 v8, 0xffff0000, v8
	v_lshlrev_b32_e32 v26, 16, v9
	v_and_b32_e32 v9, 0xffff0000, v9
	v_mul_f32_e32 v6, v6, v10
	v_mul_f32_e32 v7, v7, v11
	v_mul_f32_e32 v8, v8, v12
	v_mul_f32_e32 v9, v9, v13
	v_mul_f32_e32 v5, v23, v5
	v_mul_f32_e32 v10, v24, v20
	v_mul_f32_e32 v11, v25, v21
	v_mul_f32_e32 v12, v26, v22
	v_cvt_pk_bf16_f32 v6, v5, v6
	v_cvt_pk_bf16_f32 v7, v10, v7
	v_cvt_pk_bf16_f32 v8, v11, v8
	v_cvt_pk_bf16_f32 v9, v12, v9
	global_store_dwordx4 v[16:17], v[6:9], off
	ds_read_b128 v[10:13], v4 offset:3264
	s_waitcnt lgkmcnt(0)
	v_lshlrev_b32_e32 v4, 16, v10
	v_and_b32_e32 v5, 0xffff0000, v10
	v_lshlrev_b32_e32 v10, 16, v11
	v_and_b32_e32 v11, 0xffff0000, v11
	v_lshlrev_b32_e32 v16, 16, v12
	v_and_b32_e32 v12, 0xffff0000, v12
	v_lshlrev_b32_e32 v17, 16, v13
	v_and_b32_e32 v13, 0xffff0000, v13
	s_waitcnt vmcnt(7)
	v_mov_b32_e32 v6, v252
	v_mov_b32_e32 v7, v253
	v_mov_b32_e32 v8, v254
	v_mov_b32_e32 v9, v255
	v_lshlrev_b32_e32 v18, 16, v6
	v_and_b32_e32 v6, 0xffff0000, v6
	v_lshlrev_b32_e32 v19, 16, v7
	v_and_b32_e32 v7, 0xffff0000, v7
	v_lshlrev_b32_e32 v20, 16, v8
	v_and_b32_e32 v8, 0xffff0000, v8
	v_lshlrev_b32_e32 v21, 16, v9
	v_and_b32_e32 v9, 0xffff0000, v9
	v_mul_f32_e32 v4, v18, v4
	v_mul_f32_e32 v5, v6, v5
	v_mul_f32_e32 v6, v19, v10
	v_mul_f32_e32 v7, v7, v11
	v_mul_f32_e32 v10, v20, v16
	v_mul_f32_e32 v8, v8, v12
	v_mul_f32_e32 v11, v21, v17
	v_mul_f32_e32 v9, v9, v13
	v_cvt_pk_bf16_f32 v4, v4, v5
	v_cvt_pk_bf16_f32 v5, v6, v7
	v_cvt_pk_bf16_f32 v6, v10, v8
	v_cvt_pk_bf16_f32 v7, v11, v9
	global_store_dwordx4 v[2:3], v[4:7], off
	s_waitcnt lgkmcnt(0)
	s_and_saveexec_b64 s[4:5], vcc
	s_cbranch_execz .LBB0_224
	s_mov_b32 s69, s15
	s_lshl_b64 s[70:71], s[68:69], 2
	s_add_u32 s70, s12, s70
	s_addc_u32 s71, s13, s71
	global_load_dword v4, v183, s[70:71]
	v_lshl_add_u64 v[2:3], s[12:13], 0, v[184:185]
	s_mov_b64 s[70:71], 0
	v_mov_b32_e32 v5, v204
	v_mov_b32_e32 v6, v239

; #define PH_IDS() int tid = threadIdx.x; asm volatile("" : "+v"(tid)); const int lane = tid & 63
; __global__ void __launch_bounds__(NWAVES * 64, 2) fwd_mega(Args args) {
;     ...
;         if (vcu & 1) { fa::fox_phase((char*)lds_raw, FT, vcu, G); __syncthreads(); { PH_IDS(); v4u vin[4];
;                 if (vcu < 2048) { const v4u* vp = (const v4u*)(VA + (size_t)((vcu >> 3) * 128 + (tid >> 2)) * 1024 + (vcu & 7) * 128 + (tid & 3) * 32);
; #pragma unroll
;                     for (int i = 0; i < 4; ++i) vin[i] = vp[i]; }
;                 for (int it = vcu; it < 2048; it += G) { const int itn = it + G; sgu_item(lds, VA, AO, ZA, WSM, args.in[3], args.in[4], args.in[6], it >> 3, it & 7, tid, lane, wave, vin, itn >> 3, itn & 7, itn < 2048); } } }
;         else { { PH_IDS(); v4u vin[4];
;                 if (vcu < 2048) { const v4u* vp = (const v4u*)(VA + (size_t)((vcu >> 3) * 128 + (tid >> 2)) * 1024 + (vcu & 7) * 128 + (tid & 3) * 32);
; #pragma unroll
;                     for (int i = 0; i < 4; ++i) vin[i] = vp[i]; }
;                 for (int it = vcu; it < 2048; it += G) { const int itn = it + G; sgu_item(lds, VA, AO, ZA, WSM, args.in[3], args.in[4], args.in[6], it >> 3, it & 7, tid, lane, wave, vin, itn >> 3, itn & 7, itn < 2048); } } __syncthreads(); fa::fox_phase((char*)lds_raw, FT, vcu, G); }
.LBB0_263:
	s_waitcnt vmcnt(0)
	s_barrier
	s_bitcmp1_b32 s86, 0
	s_cbranch_scc0 .LBB0_324

; #define PH_IDS() int tid = threadIdx.x; asm volatile("" : "+v"(tid)); const int lane = tid & 63
; __global__ void __launch_bounds__(NWAVES * 64, 2) fwd_mega(Args args) {
;     ...
;         else { { PH_IDS(); v4u vin[4];
;                 if (vcu < 2048) { const v4u* vp = (const v4u*)(VA + (size_t)((vcu >> 3) * 128 + (tid >> 2)) * 1024 + (vcu & 7) * 128 + (tid & 3) * 32);
; #pragma unroll
;                     for (int i = 0; i < 4; ++i) vin[i] = vp[i]; }
;                 for (int it = vcu; it < 2048; it += G) { const int itn = it + G; sgu_item(lds, VA, AO, ZA, WSM, args.in[3], args.in[4], args.in[6], it >> 3, it & 7, tid, lane, wave, vin, itn >> 3, itn & 7, itn < 2048); } } __syncthreads(); fa::fox_phase((char*)lds_raw, FT, vcu, G); }
.Lsgu_done:
	s_bitcmp1_b32 s86, 0
	s_cbranch_scc1 .LBB0_324
	s_waitcnt vmcnt(0)
	s_barrier
	s_branch .Lattn_entry

; __device__ __forceinline__ unsigned cvt_pk_bf16(float lo, float hi) { unsigned r; asm volatile("v_cvt_pk_bf16_f32 %0, %1, %2" : "=v"(r) : "v"(lo), "v"(hi)); return r; }
; __device__ __forceinline__ float bf_lo(unsigned w) { return __uint_as_float(w << 16); }
; __device__ __forceinline__ float bf_hi(unsigned w) { return __uint_as_float(w & 0xffff0000u); }
;     __device__ __forceinline__ void operator()(const f32x4 (&acc)[2][2][4][2], const Unit& u, int wr, int wc, int fr, int fq) const {
;         const int row0 = u.pm * BM + wr * 64 + fr, col0 = u.pn * BM + wc * 32 + 8 * fq;
; #pragma unroll
;         for (int ai = 0; ai < 2; ++ai)
; #pragma unroll
;             for (int m = 0; m < 4; ++m) { const size_t off = (size_t)(row0 + ai * HALF + m * 16) * 1024 + col0;
; #pragma unroll
;                 for (int bj = 0; bj < 2; ++bj) { const u32x4 b = *(const u32x4*)(GB + off + bj * HALF);
;                     const f32x4 v0 = acc[ai][bj][m][0], v1 = acc[ai][bj][m][1];
;                     u32x4 w; w.x = cvt_pk_bf16(v0[0] * bf_lo(b.x), v0[1] * bf_hi(b.x)); w.y = cvt_pk_bf16(v0[2] * bf_lo(b.y), v0[3] * bf_hi(b.y));
;                     w.z = cvt_pk_bf16(v1[0] * bf_lo(b.z), v1[1] * bf_hi(b.z)); w.w = cvt_pk_bf16(v1[2] * bf_lo(b.w), v1[3] * bf_hi(b.w));
;                     *(u32x4*)(MG + off + bj * HALF) = w; } }
;     }
.LBB0_480:
	v_add_u32_e32 v136, s49, v175
	v_or_b32_e32 v134, s85, v177
	v_ashrrev_i32_e32 v137, 31, v136
	v_ashrrev_i32_e32 v135, 31, v134
	v_lshlrev_b64 v[4:5], 10, v[136:137]
	v_lshl_add_u64 v[4:5], v[4:5], 0, v[134:135]
	v_lshlrev_b64 v[4:5], 1, v[4:5]
	v_lshl_add_u64 v[142:143], s[50:51], 0, v[4:5]
	v_mov_b32_e32 v182, 0x8000
	v_mov_b32_e32 v183, 0
	v_mov_b32_e32 v184, 0x28000
	v_mov_b32_e32 v185, 0
	v_mov_b32_e32 v180, v142
	v_mov_b32_e32 v181, v143
	global_load_dwordx4 v[192:195], v[180:181], off
	global_load_dwordx4 v[196:199], v[180:181], off offset:256
	v_lshl_add_u64 v[180:181], v[180:181], 0, v[182:183]
	global_load_dwordx4 v[200:203], v[180:181], off
	global_load_dwordx4 v[204:207], v[180:181], off offset:256
	v_lshl_add_u64 v[180:181], v[180:181], 0, v[182:183]
	global_load_dwordx4 v[208:211], v[180:181], off
	global_load_dwordx4 v[212:215], v[180:181], off offset:256
	v_lshl_add_u64 v[180:181], v[180:181], 0, v[182:183]
	global_load_dwordx4 v[216:219], v[180:181], off
	global_load_dwordx4 v[220:223], v[180:181], off offset:256
	v_lshl_add_u64 v[180:181], v[180:181], 0, v[184:185]
	global_load_dwordx4 v[224:227], v[180:181], off
	global_load_dwordx4 v[228:231], v[180:181], off offset:256
	v_lshl_add_u64 v[180:181], v[180:181], 0, v[182:183]
	global_load_dwordx4 v[232:235], v[180:181], off
	global_load_dwordx4 v[236:239], v[180:181], off offset:256
	v_lshl_add_u64 v[180:181], v[180:181], 0, v[182:183]
	global_load_dwordx4 v[240:243], v[180:181], off
	global_load_dwordx4 v[244:247], v[180:181], off offset:256
	v_lshl_add_u64 v[180:181], v[180:181], 0, v[182:183]
	global_load_dwordx4 v[248:251], v[180:181], off
	global_load_dwordx4 v[252:255], v[180:181], off offset:256
	s_andn2_b64 vcc, exec, s[4:5]
	s_mov_b64 s[4:5], -1
	s_waitcnt vmcnt(15)
	v_mov_b32_e32 v138, v192
	v_mov_b32_e32 v139, v193
	v_mov_b32_e32 v140, v194
	v_mov_b32_e32 v141, v195
	v_lshlrev_b32_e32 v3, 16, v138
	v_and_b32_e32 v137, 0xffff0000, v138
	v_lshlrev_b32_e32 v138, 16, v139
	v_and_b32_e32 v139, 0xffff0000, v139
	v_lshlrev_b32_e32 v144, 16, v140
	v_lshlrev_b32_e32 v145, 16, v141
	v_and_b32_e32 v141, 0xffff0000, v141
	v_and_b32_e32 v140, 0xffff0000, v140
	v_mul_f32_e32 v3, v130, v3
	v_mul_f32_e32 v130, v131, v137
	v_mul_f32_e32 v131, v132, v138
	v_mul_f32_e32 v132, v133, v139
	v_mul_f32_e32 v133, v126, v144
	v_mul_f32_e32 v129, v129, v141
	v_mul_f32_e32 v137, v127, v140
	v_mul_f32_e32 v138, v128, v145
	v_cvt_pk_bf16_f32 v126, v3, v130
	v_cvt_pk_bf16_f32 v127, v131, v132
	v_cvt_pk_bf16_f32 v128, v133, v137
	v_cvt_pk_bf16_f32 v129, v138, v129
	v_or_b32_e32 v138, 16, v136
	v_ashrrev_i32_e32 v139, 31, v138
	v_lshlrev_b64 v[138:139], 10, v[138:139]
	v_lshl_add_u64 v[140:141], s[34:35], 0, v[4:5]
	v_lshl_add_u64 v[138:139], v[138:139], 0, v[134:135]
	global_store_dwordx4 v[140:141], v[126:129], off
	v_lshlrev_b64 v[138:139], 1, v[138:139]
	v_lshl_add_u64 v[142:143], s[50:51], 0, v[138:139]
	s_waitcnt vmcnt(15)
	v_mov_b32_e32 v130, v196
	v_mov_b32_e32 v131, v197
	v_mov_b32_e32 v132, v198
	v_mov_b32_e32 v133, v199
	v_lshlrev_b32_e32 v3, 16, v130
	v_and_b32_e32 v126, 0xffff0000, v130
	v_lshlrev_b32_e32 v129, 16, v132
	v_and_b32_e32 v130, 0xffff0000, v132
	v_and_b32_e32 v132, 0xffff0000, v133
	v_lshlrev_b32_e32 v127, 16, v131
	v_and_b32_e32 v128, 0xffff0000, v131
	v_lshlrev_b32_e32 v131, 16, v133
	v_mul_f32_e32 v121, v121, v132
	v_mul_f32_e32 v3, v122, v3
	v_mul_f32_e32 v122, v123, v126
	v_mul_f32_e32 v123, v124, v127
	v_mul_f32_e32 v124, v125, v128
	v_mul_f32_e32 v125, v118, v129
	v_mul_f32_e32 v126, v119, v130
	v_mul_f32_e32 v127, v120, v131
	v_cvt_pk_bf16_f32 v118, v3, v122
	v_cvt_pk_bf16_f32 v119, v123, v124
	v_cvt_pk_bf16_f32 v120, v125, v126
	v_cvt_pk_bf16_f32 v121, v127, v121
	global_store_dwordx4 v[140:141], v[118:121], off offset:256
	s_waitcnt vmcnt(15)
	v_mov_b32_e32 v118, v200
	v_mov_b32_e32 v119, v201
	v_mov_b32_e32 v120, v202
	v_mov_b32_e32 v121, v203
	v_lshlrev_b32_e32 v3, 16, v118
	v_and_b32_e32 v118, 0xffff0000, v118
	v_lshlrev_b32_e32 v122, 16, v119
	v_and_b32_e32 v119, 0xffff0000, v119
	v_lshlrev_b32_e32 v123, 16, v120
	v_lshlrev_b32_e32 v124, 16, v121
	v_and_b32_e32 v121, 0xffff0000, v121
	v_and_b32_e32 v120, 0xffff0000, v120
	v_mul_f32_e32 v3, v114, v3
	v_mul_f32_e32 v114, v115, v118
	v_mul_f32_e32 v115, v116, v122
	v_mul_f32_e32 v116, v117, v119
	v_mul_f32_e32 v117, v110, v123
	v_mul_f32_e32 v113, v113, v121
	v_mul_f32_e32 v118, v111, v120
	v_mul_f32_e32 v119, v112, v124
	v_cvt_pk_bf16_f32 v110, v3, v114
	v_cvt_pk_bf16_f32 v111, v115, v116
	v_cvt_pk_bf16_f32 v112, v117, v118
	v_cvt_pk_bf16_f32 v113, v119, v113
	v_or_b32_e32 v118, 32, v136
	v_ashrrev_i32_e32 v119, 31, v118
	v_lshlrev_b64 v[118:119], 10, v[118:119]
	v_lshl_add_u64 v[120:121], s[34:35], 0, v[138:139]
	v_lshl_add_u64 v[118:119], v[118:119], 0, v[134:135]
	global_store_dwordx4 v[120:121], v[110:113], off
	v_lshlrev_b64 v[118:119], 1, v[118:119]
	v_lshl_add_u64 v[122:123], s[50:51], 0, v[118:119]
	s_waitcnt vmcnt(15)
	v_mov_b32_e32 v114, v204
	v_mov_b32_e32 v115, v205
	v_mov_b32_e32 v116, v206
	v_mov_b32_e32 v117, v207
	v_lshlrev_b32_e32 v3, 16, v114
	v_and_b32_e32 v110, 0xffff0000, v114
	v_lshlrev_b32_e32 v113, 16, v116
	v_and_b32_e32 v114, 0xffff0000, v116
	v_and_b32_e32 v116, 0xffff0000, v117
	v_lshlrev_b32_e32 v111, 16, v115
	v_and_b32_e32 v112, 0xffff0000, v115
	v_lshlrev_b32_e32 v115, 16, v117
	v_mul_f32_e32 v105, v105, v116
	v_mul_f32_e32 v3, v106, v3
	v_mul_f32_e32 v106, v107, v110
	v_mul_f32_e32 v107, v108, v111
	v_mul_f32_e32 v108, v109, v112
	v_mul_f32_e32 v109, v102, v113
	v_mul_f32_e32 v110, v103, v114
	v_mul_f32_e32 v111, v104, v115
	v_cvt_pk_bf16_f32 v102, v3, v106
	v_cvt_pk_bf16_f32 v103, v107, v108
	v_cvt_pk_bf16_f32 v104, v109, v110
	v_cvt_pk_bf16_f32 v105, v111, v105
	global_store_dwordx4 v[120:121], v[102:105], off offset:256
	s_waitcnt vmcnt(15)
; __device__ __forceinline__ unsigned cvt_pk_bf16(float lo, float hi) { unsigned r; asm volatile("v_cvt_pk_bf16_f32 %0, %1, %2" : "=v"(r) : "v"(lo), "v"(hi)); return r; }
; __device__ __forceinline__ float bf_lo(unsigned w) { return __uint_as_float(w << 16); }
; __device__ __forceinline__ float bf_hi(unsigned w) { return __uint_as_float(w & 0xffff0000u); }
;     __device__ __forceinline__ void operator()(const f32x4 (&acc)[2][2][4][2], const Unit& u, int wr, int wc, int fr, int fq) const {
;         const int row0 = u.pm * BM + wr * 64 + fr, col0 = u.pn * BM + wc * 32 + 8 * fq;
; #pragma unroll
;         for (int ai = 0; ai < 2; ++ai)
; #pragma unroll
;             for (int m = 0; m < 4; ++m) { const size_t off = (size_t)(row0 + ai * HALF + m * 16) * 1024 + col0;
; #pragma unroll
;                 for (int bj = 0; bj < 2; ++bj) { const u32x4 b = *(const u32x4*)(GB + off + bj * HALF);
;                     const f32x4 v0 = acc[ai][bj][m][0], v1 = acc[ai][bj][m][1];
;                     u32x4 w; w.x = cvt_pk_bf16(v0[0] * bf_lo(b.x), v0[1] * bf_hi(b.x)); w.y = cvt_pk_bf16(v0[2] * bf_lo(b.y), v0[3] * bf_hi(b.y));
;                     w.z = cvt_pk_bf16(v1[0] * bf_lo(b.z), v1[1] * bf_hi(b.z)); w.w = cvt_pk_bf16(v1[2] * bf_lo(b.w), v1[3] * bf_hi(b.w));
;                     *(u32x4*)(MG + off + bj * HALF) = w; } }
;     }
	v_mov_b32_e32 v102, v208
	v_mov_b32_e32 v103, v209
	v_mov_b32_e32 v104, v210
	v_mov_b32_e32 v105, v211
	v_lshlrev_b32_e32 v3, 16, v102
	v_and_b32_e32 v102, 0xffff0000, v102
	v_lshlrev_b32_e32 v106, 16, v103
	v_and_b32_e32 v103, 0xffff0000, v103
	v_lshlrev_b32_e32 v107, 16, v104
	v_lshlrev_b32_e32 v108, 16, v105
	v_and_b32_e32 v105, 0xffff0000, v105
	v_and_b32_e32 v104, 0xffff0000, v104
	v_mul_f32_e32 v3, v98, v3
	v_mul_f32_e32 v98, v99, v102
	v_mul_f32_e32 v99, v100, v106
	v_mul_f32_e32 v100, v101, v103
	v_mul_f32_e32 v101, v94, v107
	v_mul_f32_e32 v97, v97, v105
	v_mul_f32_e32 v102, v95, v104
	v_mul_f32_e32 v103, v96, v108
	v_cvt_pk_bf16_f32 v94, v3, v98
	v_cvt_pk_bf16_f32 v95, v99, v100
	v_cvt_pk_bf16_f32 v96, v101, v102
	v_cvt_pk_bf16_f32 v97, v103, v97
	v_or_b32_e32 v102, 48, v136
	v_ashrrev_i32_e32 v103, 31, v102
	v_lshlrev_b64 v[102:103], 10, v[102:103]
	v_lshl_add_u64 v[104:105], s[34:35], 0, v[118:119]
	v_lshl_add_u64 v[102:103], v[102:103], 0, v[134:135]
	global_store_dwordx4 v[104:105], v[94:97], off
	v_lshlrev_b64 v[102:103], 1, v[102:103]
	v_lshl_add_u64 v[106:107], s[50:51], 0, v[102:103]
	s_waitcnt vmcnt(15)
	v_mov_b32_e32 v98, v212
	v_mov_b32_e32 v99, v213
	v_mov_b32_e32 v100, v214
	v_mov_b32_e32 v101, v215
	v_lshlrev_b32_e32 v3, 16, v98
	v_and_b32_e32 v94, 0xffff0000, v98
	v_lshlrev_b32_e32 v97, 16, v100
	v_and_b32_e32 v98, 0xffff0000, v100
	v_and_b32_e32 v100, 0xffff0000, v101
	v_lshlrev_b32_e32 v95, 16, v99
	v_and_b32_e32 v96, 0xffff0000, v99
	v_lshlrev_b32_e32 v99, 16, v101
	v_mul_f32_e32 v89, v89, v100
	v_mul_f32_e32 v3, v90, v3
	v_mul_f32_e32 v90, v91, v94
	v_mul_f32_e32 v91, v92, v95
	v_mul_f32_e32 v92, v93, v96
	v_mul_f32_e32 v93, v86, v97
	v_mul_f32_e32 v94, v87, v98
	v_mul_f32_e32 v95, v88, v99
	v_cvt_pk_bf16_f32 v86, v3, v90
	v_cvt_pk_bf16_f32 v87, v91, v92
	v_cvt_pk_bf16_f32 v88, v93, v94
	v_cvt_pk_bf16_f32 v89, v95, v89
	global_store_dwordx4 v[104:105], v[86:89], off offset:256
	s_waitcnt vmcnt(15)
	v_mov_b32_e32 v86, v216
	v_mov_b32_e32 v87, v217
	v_mov_b32_e32 v88, v218
	v_mov_b32_e32 v89, v219
	v_lshlrev_b32_e32 v3, 16, v86
	v_and_b32_e32 v86, 0xffff0000, v86
	v_lshlrev_b32_e32 v90, 16, v87
	v_and_b32_e32 v87, 0xffff0000, v87
	v_lshlrev_b32_e32 v91, 16, v88
	v_lshlrev_b32_e32 v92, 16, v89
	v_and_b32_e32 v89, 0xffff0000, v89
	v_and_b32_e32 v88, 0xffff0000, v88
	v_mul_f32_e32 v3, v82, v3
	v_mul_f32_e32 v82, v83, v86
	v_mul_f32_e32 v83, v84, v90
	v_mul_f32_e32 v84, v85, v87
	v_mul_f32_e32 v85, v78, v91
	v_mul_f32_e32 v81, v81, v89
	v_mul_f32_e32 v86, v79, v88
	v_mul_f32_e32 v87, v80, v92
	v_cvt_pk_bf16_f32 v78, v3, v82
	v_cvt_pk_bf16_f32 v79, v83, v84
	v_cvt_pk_bf16_f32 v80, v85, v86
	v_cvt_pk_bf16_f32 v81, v87, v81
	v_lshl_add_u64 v[88:89], s[34:35], 0, v[102:103]
	global_store_dwordx4 v[88:89], v[78:81], off
	v_lshl_add_u64 v[86:87], v[4:5], 0, s[20:21]
	v_lshl_add_u64 v[90:91], s[50:51], 0, v[86:87]
	s_waitcnt vmcnt(15)
	v_mov_b32_e32 v82, v220
	v_mov_b32_e32 v83, v221
	v_mov_b32_e32 v84, v222
	v_mov_b32_e32 v85, v223
	v_lshlrev_b32_e32 v3, 16, v82
	v_and_b32_e32 v78, 0xffff0000, v82
	v_lshlrev_b32_e32 v81, 16, v84
	v_and_b32_e32 v82, 0xffff0000, v84
	v_and_b32_e32 v84, 0xffff0000, v85
	v_lshlrev_b32_e32 v79, 16, v83
	v_and_b32_e32 v80, 0xffff0000, v83
	v_lshlrev_b32_e32 v83, 16, v85
	v_mul_f32_e32 v73, v73, v84
	v_mul_f32_e32 v3, v74, v3
	v_mul_f32_e32 v74, v75, v78
	v_mul_f32_e32 v75, v76, v79
	v_mul_f32_e32 v76, v77, v80
	v_mul_f32_e32 v77, v70, v81
	v_mul_f32_e32 v78, v71, v82
	v_mul_f32_e32 v79, v72, v83
	v_cvt_pk_bf16_f32 v70, v3, v74
	v_cvt_pk_bf16_f32 v71, v75, v76
	v_cvt_pk_bf16_f32 v72, v77, v78
	v_cvt_pk_bf16_f32 v73, v79, v73
	global_store_dwordx4 v[88:89], v[70:73], off offset:256
	s_waitcnt vmcnt(15)
	v_mov_b32_e32 v70, v224
	v_mov_b32_e32 v71, v225
	v_mov_b32_e32 v72, v226
	v_mov_b32_e32 v73, v227
	v_lshlrev_b32_e32 v3, 16, v70
	v_and_b32_e32 v70, 0xffff0000, v70
	v_lshlrev_b32_e32 v74, 16, v71
	v_and_b32_e32 v71, 0xffff0000, v71
	v_lshlrev_b32_e32 v75, 16, v72
	v_lshlrev_b32_e32 v76, 16, v73
	v_and_b32_e32 v73, 0xffff0000, v73
	v_and_b32_e32 v72, 0xffff0000, v72
	v_mul_f32_e32 v3, v66, v3
	v_mul_f32_e32 v66, v67, v70
	v_mul_f32_e32 v67, v68, v74
	v_mul_f32_e32 v68, v69, v71
	v_mul_f32_e32 v69, v62, v75
	v_mul_f32_e32 v65, v65, v73
	v_mul_f32_e32 v70, v63, v72
	v_mul_f32_e32 v71, v64, v76
	v_cvt_pk_bf16_f32 v62, v3, v66
	v_cvt_pk_bf16_f32 v63, v67, v68
	v_cvt_pk_bf16_f32 v64, v69, v70
	v_cvt_pk_bf16_f32 v65, v71, v65
	v_lshl_add_u64 v[72:73], s[34:35], 0, v[86:87]
	global_store_dwordx4 v[72:73], v[62:65], off
	v_lshl_add_u64 v[70:71], v[4:5], 0, s[22:23]
	v_lshl_add_u64 v[74:75], s[50:51], 0, v[70:71]
	s_waitcnt vmcnt(15)
	v_mov_b32_e32 v66, v228
	v_mov_b32_e32 v67, v229
	v_mov_b32_e32 v68, v230
	v_mov_b32_e32 v69, v231
	v_lshlrev_b32_e32 v3, 16, v66
	v_and_b32_e32 v62, 0xffff0000, v66
	v_lshlrev_b32_e32 v65, 16, v68
	v_and_b32_e32 v66, 0xffff0000, v68
	v_and_b32_e32 v68, 0xffff0000, v69
	v_lshlrev_b32_e32 v63, 16, v67
	v_and_b32_e32 v64, 0xffff0000, v67
	v_lshlrev_b32_e32 v67, 16, v69
	v_mul_f32_e32 v57, v57, v68
	v_mul_f32_e32 v3, v58, v3
	v_mul_f32_e32 v58, v59, v62
	v_mul_f32_e32 v59, v60, v63
	v_mul_f32_e32 v60, v61, v64
	v_mul_f32_e32 v61, v54, v65
	v_mul_f32_e32 v62, v55, v66
	v_mul_f32_e32 v63, v56, v67
	v_cvt_pk_bf16_f32 v54, v3, v58
	v_cvt_pk_bf16_f32 v55, v59, v60
	v_cvt_pk_bf16_f32 v56, v61, v62
	v_cvt_pk_bf16_f32 v57, v63, v57
	global_store_dwordx4 v[72:73], v[54:57], off offset:256
	s_waitcnt vmcnt(15)
; __device__ __forceinline__ unsigned cvt_pk_bf16(float lo, float hi) { unsigned r; asm volatile("v_cvt_pk_bf16_f32 %0, %1, %2" : "=v"(r) : "v"(lo), "v"(hi)); return r; }
; __device__ __forceinline__ float bf_lo(unsigned w) { return __uint_as_float(w << 16); }
; __device__ __forceinline__ float bf_hi(unsigned w) { return __uint_as_float(w & 0xffff0000u); }
;     __device__ __forceinline__ void operator()(const f32x4 (&acc)[2][2][4][2], const Unit& u, int wr, int wc, int fr, int fq) const {
;         const int row0 = u.pm * BM + wr * 64 + fr, col0 = u.pn * BM + wc * 32 + 8 * fq;
; #pragma unroll
;         for (int ai = 0; ai < 2; ++ai)
; #pragma unroll
;             for (int m = 0; m < 4; ++m) { const size_t off = (size_t)(row0 + ai * HALF + m * 16) * 1024 + col0;
; #pragma unroll
;                 for (int bj = 0; bj < 2; ++bj) { const u32x4 b = *(const u32x4*)(GB + off + bj * HALF);
;                     const f32x4 v0 = acc[ai][bj][m][0], v1 = acc[ai][bj][m][1];
;                     u32x4 w; w.x = cvt_pk_bf16(v0[0] * bf_lo(b.x), v0[1] * bf_hi(b.x)); w.y = cvt_pk_bf16(v0[2] * bf_lo(b.y), v0[3] * bf_hi(b.y));
;                     w.z = cvt_pk_bf16(v1[0] * bf_lo(b.z), v1[1] * bf_hi(b.z)); w.w = cvt_pk_bf16(v1[2] * bf_lo(b.w), v1[3] * bf_hi(b.w));
;                     *(u32x4*)(MG + off + bj * HALF) = w; } }
;     }
	v_mov_b32_e32 v54, v232
	v_mov_b32_e32 v55, v233
	v_mov_b32_e32 v56, v234
	v_mov_b32_e32 v57, v235
	v_lshlrev_b32_e32 v3, 16, v54
	v_and_b32_e32 v54, 0xffff0000, v54
	v_lshlrev_b32_e32 v58, 16, v55
	v_and_b32_e32 v55, 0xffff0000, v55
	v_lshlrev_b32_e32 v59, 16, v56
	v_lshlrev_b32_e32 v60, 16, v57
	v_and_b32_e32 v57, 0xffff0000, v57
	v_and_b32_e32 v56, 0xffff0000, v56
	v_mul_f32_e32 v3, v50, v3
	v_mul_f32_e32 v50, v51, v54
	v_mul_f32_e32 v51, v52, v58
	v_mul_f32_e32 v52, v53, v55
	v_mul_f32_e32 v53, v46, v59
	v_mul_f32_e32 v49, v49, v57
	v_mul_f32_e32 v54, v47, v56
	v_mul_f32_e32 v55, v48, v60
	v_cvt_pk_bf16_f32 v46, v3, v50
	v_cvt_pk_bf16_f32 v47, v51, v52
	v_cvt_pk_bf16_f32 v48, v53, v54
	v_cvt_pk_bf16_f32 v49, v55, v49
	v_lshl_add_u64 v[56:57], s[34:35], 0, v[70:71]
	global_store_dwordx4 v[56:57], v[46:49], off
	v_lshl_add_u64 v[54:55], v[4:5], 0, s[42:43]
	v_lshl_add_u64 v[58:59], s[50:51], 0, v[54:55]
	v_lshl_add_u64 v[4:5], v[4:5], 0, s[44:45]
	s_waitcnt vmcnt(15)
	v_mov_b32_e32 v50, v236
	v_mov_b32_e32 v51, v237
	v_mov_b32_e32 v52, v238
	v_mov_b32_e32 v53, v239
	v_lshlrev_b32_e32 v3, 16, v50
	v_and_b32_e32 v46, 0xffff0000, v50
	v_lshlrev_b32_e32 v49, 16, v52
	v_and_b32_e32 v50, 0xffff0000, v52
	v_and_b32_e32 v52, 0xffff0000, v53
	v_lshlrev_b32_e32 v47, 16, v51
	v_and_b32_e32 v48, 0xffff0000, v51
	v_lshlrev_b32_e32 v51, 16, v53
	v_mul_f32_e32 v41, v41, v52
	v_mul_f32_e32 v3, v42, v3
	v_mul_f32_e32 v42, v43, v46
	v_mul_f32_e32 v43, v44, v47
	v_mul_f32_e32 v44, v45, v48
	v_mul_f32_e32 v45, v38, v49
	v_mul_f32_e32 v46, v39, v50
	v_mul_f32_e32 v47, v40, v51
	v_cvt_pk_bf16_f32 v38, v3, v42
	v_cvt_pk_bf16_f32 v39, v43, v44
	v_cvt_pk_bf16_f32 v40, v45, v46
	v_cvt_pk_bf16_f32 v41, v47, v41
	global_store_dwordx4 v[56:57], v[38:41], off offset:256
	s_waitcnt vmcnt(15)
	v_mov_b32_e32 v38, v240
	v_mov_b32_e32 v39, v241
	v_mov_b32_e32 v40, v242
	v_mov_b32_e32 v41, v243
	v_lshlrev_b32_e32 v3, 16, v38
	v_and_b32_e32 v38, 0xffff0000, v38
	v_lshlrev_b32_e32 v42, 16, v39
	v_and_b32_e32 v39, 0xffff0000, v39
	v_lshlrev_b32_e32 v43, 16, v40
	v_lshlrev_b32_e32 v44, 16, v41
	v_and_b32_e32 v41, 0xffff0000, v41
	v_and_b32_e32 v40, 0xffff0000, v40
	v_mul_f32_e32 v3, v34, v3
	v_mul_f32_e32 v34, v35, v38
	v_mul_f32_e32 v35, v36, v42
	v_mul_f32_e32 v36, v37, v39
	v_mul_f32_e32 v37, v30, v43
	v_mul_f32_e32 v33, v33, v41
	v_mul_f32_e32 v38, v31, v40
	v_mul_f32_e32 v39, v32, v44
	v_cvt_pk_bf16_f32 v30, v3, v34
	v_cvt_pk_bf16_f32 v31, v35, v36
	v_cvt_pk_bf16_f32 v32, v37, v38
	v_cvt_pk_bf16_f32 v33, v39, v33
	v_lshl_add_u64 v[38:39], s[34:35], 0, v[54:55]
	global_store_dwordx4 v[38:39], v[30:33], off
	v_lshl_add_u64 v[40:41], s[50:51], 0, v[4:5]
	s_waitcnt vmcnt(15)
	v_mov_b32_e32 v34, v244
	v_mov_b32_e32 v35, v245
	v_mov_b32_e32 v36, v246
	v_mov_b32_e32 v37, v247
	v_lshlrev_b32_e32 v3, 16, v34
	v_and_b32_e32 v30, 0xffff0000, v34
	v_lshlrev_b32_e32 v33, 16, v36
	v_and_b32_e32 v34, 0xffff0000, v36
	v_and_b32_e32 v36, 0xffff0000, v37
	v_lshlrev_b32_e32 v31, 16, v35
	v_and_b32_e32 v32, 0xffff0000, v35
	v_lshlrev_b32_e32 v35, 16, v37
	v_mul_f32_e32 v25, v25, v36
	v_mul_f32_e32 v3, v26, v3
	v_mul_f32_e32 v26, v27, v30
	v_mul_f32_e32 v27, v28, v31
	v_mul_f32_e32 v28, v29, v32
	v_mul_f32_e32 v29, v22, v33
	v_mul_f32_e32 v30, v23, v34
	v_mul_f32_e32 v31, v24, v35
	v_cvt_pk_bf16_f32 v22, v3, v26
	v_cvt_pk_bf16_f32 v23, v27, v28
	v_cvt_pk_bf16_f32 v24, v29, v30
	v_cvt_pk_bf16_f32 v25, v31, v25
	global_store_dwordx4 v[38:39], v[22:25], off offset:256
	s_waitcnt vmcnt(15)
	v_mov_b32_e32 v22, v248
	v_mov_b32_e32 v23, v249
	v_mov_b32_e32 v24, v250
	v_mov_b32_e32 v25, v251
	v_lshlrev_b32_e32 v3, 16, v22
	v_and_b32_e32 v22, 0xffff0000, v22
	v_lshlrev_b32_e32 v26, 16, v23
	v_and_b32_e32 v23, 0xffff0000, v23
	v_lshlrev_b32_e32 v27, 16, v24
	v_lshlrev_b32_e32 v28, 16, v25
	v_and_b32_e32 v25, 0xffff0000, v25
	v_and_b32_e32 v24, 0xffff0000, v24
	v_mul_f32_e32 v3, v18, v3
	v_mul_f32_e32 v18, v19, v22
	v_mul_f32_e32 v19, v20, v26
	v_mul_f32_e32 v20, v21, v23
	v_mul_f32_e32 v21, v14, v27
	v_mul_f32_e32 v17, v17, v25
	v_mul_f32_e32 v22, v15, v24
	v_mul_f32_e32 v23, v16, v28
	v_cvt_pk_bf16_f32 v14, v3, v18
	v_cvt_pk_bf16_f32 v15, v19, v20
	v_cvt_pk_bf16_f32 v16, v21, v22
	v_cvt_pk_bf16_f32 v17, v23, v17
	v_lshl_add_u64 v[22:23], s[34:35], 0, v[4:5]
	global_store_dwordx4 v[22:23], v[14:17], off
	s_waitcnt vmcnt(15)
	v_mov_b32_e32 v18, v252
	v_mov_b32_e32 v19, v253
	v_mov_b32_e32 v20, v254
	v_mov_b32_e32 v21, v255
	v_and_b32_e32 v4, 0xffff0000, v18
	v_lshlrev_b32_e32 v5, 16, v19
	v_lshlrev_b32_e32 v15, 16, v20
	v_and_b32_e32 v16, 0xffff0000, v20
	v_lshlrev_b32_e32 v3, 16, v18
	v_and_b32_e32 v14, 0xffff0000, v19
	v_lshlrev_b32_e32 v17, 16, v21
	v_and_b32_e32 v18, 0xffff0000, v21
	v_mul_f32_e32 v4, v11, v4
	v_mul_f32_e32 v5, v12, v5
	v_mul_f32_e32 v6, v6, v15
	v_mul_f32_e32 v7, v7, v16
	v_mul_f32_e32 v3, v10, v3
	v_mul_f32_e32 v10, v13, v14
	v_mul_f32_e32 v8, v8, v17
	v_mul_f32_e32 v9, v9, v18
	v_cvt_pk_bf16_f32 v4, v3, v4
	v_cvt_pk_bf16_f32 v5, v5, v10
	v_cvt_pk_bf16_f32 v6, v6, v7
	v_cvt_pk_bf16_f32 v7, v8, v9
	global_store_dwordx4 v[22:23], v[4:7], off offset:256
	s_cbranch_vccnz .LBB0_467
	s_andn2_b64 vcc, exec, s[8:9]
	s_cbranch_vccnz .LBB0_466
	s_barrier
	s_branch .LBB0_466
